# layer-1 up-projection phase: workgroups owning 5 (not 6) tiles start half a tile later so their epilogue store bursts interleave with the others
# speedup vs baseline: 1.0595x; 1.0088x over previous
; #define LAS __attribute__((address_space(3)))
; template <class T> __device__ __forceinline__ T* uptr(T* q) { const unsigned long long v = (unsigned long long)q; const unsigned lo = __builtin_amdgcn_readfirstlane((unsigned)v), hi = __builtin_amdgcn_readfirstlane((unsigned)(v >> 32)); return (T*)(((unsigned long long)hi << 32) | lo); }
; __device__ __forceinline__ bool gemm_phase(LAS unsigned char* lds, int l, int sub, int gi, bool dry = false) {
;     GD g; if (!make_gd((LAS const Params*)(lds + PRM_OFF), l, sub, gi, g)) return false;
;     g.A = uptr(g.A); g.Bt = uptr(g.Bt); g.lda = __builtin_amdgcn_readfirstlane(g.lda); g.ldb = __builtin_amdgcn_readfirstlane(g.ldb); g.K = __builtin_amdgcn_readfirstlane(g.K);
;     g.nM = __builtin_amdgcn_readfirstlane(g.nM); g.splitk = __builtin_amdgcn_readfirstlane(g.splitk); g.xctx = __builtin_amdgcn_readfirstlane(g.xctx); g.sctx = __builtin_amdgcn_readfirstlane(g.sctx); g.nN = __builtin_amdgcn_readfirstlane(g.nN); g.mode = __builtin_amdgcn_readfirstlane(g.mode);
.LBB0_243:
	s_cmp_lg_u32 s17, 6
	s_cbranch_scc1 .Lmy_nodelay
	v_readlane_b32 s4, v255, 0
	s_nop 3
	s_cmp_lg_u32 s4, 1
	s_cbranch_scc1 .Lmy_nodelay
	s_cmp_lt_u32 s26, 128
	s_cbranch_scc1 .Lmy_nodelay
	s_sleep 127
	s_sleep 127
	s_sleep 127
	s_sleep 127
